# k43: k36 + nt hint on the once-read gate rows loaded in the attention epilogue
# baseline (speedup 1.0000x reference)
.LBB0_1327:
	s_or_b64 exec, exec, s[4:5]
	v_readlane_b32 s56, v254, 30
	s_waitcnt lgkmcnt(0)
	v_lshlrev_b32_e32 v64, 2, v230
	v_readlane_b32 s68, v254, 42
	v_readlane_b32 s69, v254, 43
	s_nop 4
	global_load_dword v82, v64, s[68:69]
	global_load_dword v83, v64, s[68:69] offset:128
	global_load_dword v84, v64, s[68:69] offset:256
	global_load_dword v85, v64, s[68:69] offset:384
	s_lshl_b32 s4, s48, 13
	s_lshl_b64 s[6:7], s[10:11], 1
	ds_read_b128 v[78:81], v96 offset:128
	ds_read_b128 v[72:75], v96 offset:160
	ds_read_b128 v[68:71], v96 offset:192
	ds_read_b128 v[64:67], v96 offset:224
	s_add_u32 s8, s50, s6
	s_addc_u32 s9, s51, s7
	s_add_i32 s4, s4, 0
	s_add_i32 s4, s4, 0x12800
	s_waitcnt lgkmcnt(3)
	v_rcp_f32_e32 v78, v78
	v_rcp_f32_e32 v79, v79
	v_lshlrev_b32_e32 v76, 8, v212
	v_lshl_add_u32 v77, v230, 1, s4
	v_add_u32_e32 v86, v77, v76
	ds_read_u16 v87, v86
	ds_read_u16 v88, v86 offset:64
	ds_read_u16 v89, v86 offset:128
	ds_read_u16 v90, v86 offset:192
	ds_read_u16 v91, v86 offset:256
	ds_read_u16 v92, v86 offset:320
	ds_read_u16 v93, v86 offset:384
	ds_read_u16 v94, v86 offset:448
	v_mul_f32_e32 v32, v32, v78
	v_mul_f32_e32 v49, v49, v79
	v_mul_f32_e32 v33, v33, v79
	v_mul_f32_e32 v17, v17, v79
	v_mul_f32_e32 v1, v1, v79
	s_waitcnt lgkmcnt(6)
	v_lshlrev_b32_e32 v79, 16, v88
	v_mul_f32_e32 v48, v48, v78
	v_mul_f32_e32 v16, v16, v78
	v_mul_f32_e32 v0, v0, v78
	v_lshlrev_b32_e32 v78, 16, v87
	s_waitcnt lgkmcnt(5)
	v_lshlrev_b32_e32 v87, 16, v89
	s_waitcnt lgkmcnt(3)
	v_lshlrev_b32_e32 v89, 16, v91
	v_fma_f32 v32, -v229, v32, v79
	v_fma_f32 v48, -v229, v48, v78
	v_fma_f32 v16, -v229, v16, v87
	v_fma_f32 v87, -v229, v49, v89
	v_mul_f32_e32 v49, v32, v32
	v_lshlrev_b32_e32 v88, 16, v90
	v_fmac_f32_e32 v49, v48, v48
	v_fma_f32 v0, -v229, v0, v88
	v_fmac_f32_e32 v49, v16, v16
	v_fmac_f32_e32 v49, v0, v0
	s_waitcnt lgkmcnt(2)
	v_lshlrev_b32_e32 v90, 16, v92
	v_fma_f32 v33, -v229, v33, v90
	v_add_f32_dpp v49, v49, v49 quad_perm:[1,0,3,2] row_mask:0xf bank_mask:0xf bound_ctrl:1
	s_waitcnt lgkmcnt(1)
	v_lshlrev_b32_e32 v91, 16, v93
	v_mul_f32_e32 v79, v33, v33
	v_add_f32_dpp v49, v49, v49 quad_perm:[2,3,0,1] row_mask:0xf bank_mask:0xf bound_ctrl:1
	s_waitcnt lgkmcnt(0)
	v_lshlrev_b32_e32 v92, 16, v94
	v_fma_f32 v17, -v229, v17, v91
	v_add_f32_dpp v49, v49, v49 row_half_mirror row_mask:0xf bank_mask:0xf bound_ctrl:1
	v_fmac_f32_e32 v79, v87, v87
	v_fma_f32 v1, -v229, v1, v92
	v_add_f32_dpp v49, v49, v49 row_mirror row_mask:0xf bank_mask:0xf bound_ctrl:1
	ds_swizzle_b32 v78, v49 offset:swizzle(SWAP,16)
	v_fmac_f32_e32 v79, v17, v17
	v_fmac_f32_e32 v79, v1, v1
	v_rcp_f32_e32 v80, v80
	v_rcp_f32_e32 v81, v81
	s_waitcnt lgkmcnt(0)
	v_add_f32_e32 v49, v49, v78
	v_fmamk_f32 v49, v49, 0x3c000000, v227
	v_rsq_f32_e32 v88, v49
	v_add_f32_dpp v89, v79, v79 quad_perm:[1,0,3,2] row_mask:0xf bank_mask:0xf bound_ctrl:1
	v_mul_f32_e32 v34, v34, v80
	v_mul_f32_e32 v50, v50, v80
	v_mul_f32_e32 v90, v48, v88
	v_mul_f32_e32 v32, v32, v88
	v_mul_f32_e32 v16, v16, v88
	v_mul_f32_e32 v0, v0, v88
	v_mul_f32_e32 v18, v18, v80
	v_mul_f32_e32 v2, v2, v80
	v_mul_f32_e32 v19, v19, v81
	v_mul_f32_e32 v3, v3, v81
	v_lshlrev_b32_e32 v212, 4, v241
	s_movk_i32 s5, 0x2000
	s_add_u32 s6, s52, s6
	s_addc_u32 s7, s72, s7
	s_add_i32 s88, s88, 1
	s_cmp_eq_u32 s88, 8
	v_readlane_b32 s57, v254, 31
	v_readlane_b32 s58, v254, 32
	v_readlane_b32 s59, v254, 33
	v_readlane_b32 s60, v254, 34
	s_waitcnt vmcnt(3)
	v_mul_f32_e32 v79, 0x3f24fd5c, v82
	s_waitcnt vmcnt(2)
	v_mul_f32_e32 v78, 0x3f24fd5c, v83
	v_mul_f32_e32 v82, v79, v90
	v_mul_f32_e32 v32, v78, v32
	v_cvt_pk_bf16_f32 v82, v82, s0
	v_cvt_pk_bf16_f32 v32, v32, s0
	ds_write_b16 v86, v82
	ds_write_b16 v86, v32 offset:64
	v_add_f32_dpp v32, v89, v89 quad_perm:[2,3,0,1] row_mask:0xf bank_mask:0xf bound_ctrl:1
	s_waitcnt vmcnt(1)
	v_mul_f32_e32 v49, 0x3f24fd5c, v84
	v_mul_f32_e32 v16, v49, v16
	v_add_f32_dpp v32, v32, v32 row_half_mirror row_mask:0xf bank_mask:0xf bound_ctrl:1
	v_cvt_pk_bf16_f32 v16, v16, s0
	ds_write_b16 v86, v16 offset:128
	v_add_f32_dpp v32, v32, v32 row_mirror row_mask:0xf bank_mask:0xf bound_ctrl:1
	ds_swizzle_b32 v82, v32 offset:swizzle(SWAP,16)
	s_waitcnt vmcnt(0)
	v_mul_f32_e32 v48, 0x3f24fd5c, v85
	v_mul_f32_e32 v0, v48, v0
	v_cvt_pk_bf16_f32 v0, v0, s0
	ds_write_b16 v86, v0 offset:192
	s_waitcnt lgkmcnt(1)
	v_add_f32_e32 v16, v32, v82
	v_fmamk_f32 v16, v16, 0x3c000000, v227
	v_rsq_f32_e32 v16, v16
	v_readlane_b32 s61, v254, 35
	v_readlane_b32 s62, v254, 36
	v_readlane_b32 s63, v254, 37
	v_mul_f32_e32 v0, v87, v16
	v_mul_f32_e32 v0, v79, v0
	v_cvt_pk_bf16_f32 v0, v0, s0
	ds_write_b16 v86, v0 offset:256
	v_mul_f32_e32 v0, v33, v16
	v_mul_f32_e32 v0, v78, v0
	v_cvt_pk_bf16_f32 v0, v0, s0
	ds_write_b16 v86, v0 offset:320
	v_mul_f32_e32 v0, v17, v16
	ds_read_u16 v17, v86 offset:512
	ds_read_u16 v32, v86 offset:576
	ds_read_u16 v33, v86 offset:640
	ds_read_u16 v82, v86 offset:704
	ds_read_u16 v83, v86 offset:768
	ds_read_u16 v84, v86 offset:832
	ds_read_u16 v85, v86 offset:896
	ds_read_u16 v87, v86 offset:960
	s_waitcnt lgkmcnt(6)
	v_lshlrev_b32_e32 v32, 16, v32
	v_lshlrev_b32_e32 v17, 16, v17
	v_fma_f32 v32, -v229, v34, v32
	v_fma_f32 v17, -v229, v50, v17
	v_mul_f32_e32 v34, v32, v32
	s_waitcnt lgkmcnt(5)
	v_lshlrev_b32_e32 v33, 16, v33
	v_fmac_f32_e32 v34, v17, v17
	v_fma_f32 v18, -v229, v18, v33
	s_waitcnt lgkmcnt(4)
	v_lshlrev_b32_e32 v33, 16, v82
	v_fmac_f32_e32 v34, v18, v18
	v_fma_f32 v2, -v229, v2, v33
	v_fmac_f32_e32 v34, v2, v2
	v_mul_f32_e32 v0, v49, v0
	v_cvt_pk_bf16_f32 v0, v0, s0
	v_add_f32_dpp v33, v34, v34 quad_perm:[1,0,3,2] row_mask:0xf bank_mask:0xf bound_ctrl:1
	ds_write_b16 v86, v0 offset:384
	v_mul_f32_e32 v0, v1, v16
	v_add_f32_dpp v33, v33, v33 quad_perm:[2,3,0,1] row_mask:0xf bank_mask:0xf bound_ctrl:1
	v_mul_f32_e32 v0, v48, v0
	v_cvt_pk_bf16_f32 v0, v0, s0
	v_add_f32_dpp v33, v33, v33 row_half_mirror row_mask:0xf bank_mask:0xf bound_ctrl:1
	ds_write_b16 v86, v0 offset:448
	s_waitcnt lgkmcnt(5)
	v_lshlrev_b32_e32 v16, 16, v83
	v_add_f32_dpp v33, v33, v33 row_mirror row_mask:0xf bank_mask:0xf bound_ctrl:1
	ds_swizzle_b32 v34, v33 offset:swizzle(SWAP,16)
	v_readlane_b32 s64, v254, 38
	v_readlane_b32 s65, v254, 39
	v_readlane_b32 s66, v254, 40
	v_readlane_b32 s67, v254, 41
	s_waitcnt lgkmcnt(0)
	v_add_f32_e32 v1, v33, v34
	v_fmamk_f32 v1, v1, 0x3c000000, v227
	v_rsq_f32_e32 v1, v1
	v_readlane_b32 s70, v254, 44
	v_readlane_b32 s71, v254, 45
	v_mul_f32_e32 v0, v17, v1
	v_mul_f32_e32 v0, v79, v0
	v_cvt_pk_bf16_f32 v0, v0, s0
	ds_write_b16 v86, v0 offset:512
	v_mul_f32_e32 v0, v32, v1
	v_mul_f32_e32 v0, v78, v0
	v_cvt_pk_bf16_f32 v0, v0, s0
	v_mul_f32_e32 v17, v51, v81
	ds_write_b16 v86, v0 offset:576
	v_mul_f32_e32 v0, v18, v1
	v_fma_f32 v16, -v229, v17, v16
	v_lshlrev_b32_e32 v17, 16, v84
	v_mul_f32_e32 v18, v35, v81
	v_fma_f32 v17, -v229, v18, v17
	v_mul_f32_e32 v18, v17, v17
	v_lshlrev_b32_e32 v32, 16, v85
	v_fmac_f32_e32 v18, v16, v16
	v_fma_f32 v19, -v229, v19, v32
	v_lshlrev_b32_e32 v32, 16, v87
	v_fmac_f32_e32 v18, v19, v19
	v_fma_f32 v3, -v229, v3, v32
	v_fmac_f32_e32 v18, v3, v3
	v_mul_f32_e32 v0, v49, v0
	v_cvt_pk_bf16_f32 v0, v0, s0
	v_add_f32_dpp v18, v18, v18 quad_perm:[1,0,3,2] row_mask:0xf bank_mask:0xf bound_ctrl:1
	ds_write_b16 v86, v0 offset:640
	v_mul_f32_e32 v0, v2, v1
	v_add_f32_dpp v18, v18, v18 quad_perm:[2,3,0,1] row_mask:0xf bank_mask:0xf bound_ctrl:1
	v_mul_f32_e32 v0, v48, v0
	v_cvt_pk_bf16_f32 v0, v0, s0
	v_add_f32_dpp v18, v18, v18 row_half_mirror row_mask:0xf bank_mask:0xf bound_ctrl:1
	ds_write_b16 v86, v0 offset:704
	v_rcp_f32_e32 v2, v72
	v_add_f32_dpp v18, v18, v18 row_mirror row_mask:0xf bank_mask:0xf bound_ctrl:1
	ds_swizzle_b32 v32, v18 offset:swizzle(SWAP,16)
	s_waitcnt lgkmcnt(0)
	v_add_f32_e32 v1, v18, v32
	v_fmamk_f32 v1, v1, 0x3c000000, v227
	v_rsq_f32_e32 v1, v1
	v_mul_f32_e32 v18, v52, v2
	v_mul_f32_e32 v0, v16, v1
	v_mul_f32_e32 v0, v79, v0
	v_cvt_pk_bf16_f32 v0, v0, s0
	ds_write_b16 v86, v0 offset:768
	v_mul_f32_e32 v0, v17, v1
	v_mul_f32_e32 v0, v78, v0
	v_cvt_pk_bf16_f32 v0, v0, s0
	ds_write_b16 v86, v0 offset:832
	v_mul_f32_e32 v0, v19, v1
	v_mul_f32_e32 v0, v49, v0
	v_cvt_pk_bf16_f32 v0, v0, s0
	ds_write_b16 v86, v0 offset:896
	v_mul_f32_e32 v0, v3, v1
	v_mul_f32_e32 v0, v48, v0
	v_cvt_pk_bf16_f32 v0, v0, s0
	ds_write_b16 v86, v0 offset:960
	v_or_b32_e32 v0, 0x800, v76
	v_add_u32_e32 v0, v77, v0
	ds_read_u16 v1, v0
	ds_read_u16 v3, v0 offset:64
	ds_read_u16 v16, v0 offset:128
	ds_read_u16 v17, v0 offset:192
	v_mul_f32_e32 v19, v20, v2
	s_waitcnt lgkmcnt(2)
	v_lshlrev_b32_e32 v3, 16, v3
	v_lshlrev_b32_e32 v1, 16, v1
	v_fma_f32 v1, -v229, v18, v1
	v_mul_f32_e32 v18, v36, v2
	v_fma_f32 v3, -v229, v18, v3
	v_mul_f32_e32 v18, v3, v3
	s_waitcnt lgkmcnt(1)
	v_lshlrev_b32_e32 v16, 16, v16
	v_fmac_f32_e32 v18, v1, v1
	v_fma_f32 v16, -v229, v19, v16
	s_waitcnt lgkmcnt(0)
	v_lshlrev_b32_e32 v17, 16, v17
	v_mul_f32_e32 v2, v4, v2
	v_fmac_f32_e32 v18, v16, v16
	v_fma_f32 v2, -v229, v2, v17
	v_fmac_f32_e32 v18, v2, v2
	s_nop 1
	v_add_f32_dpp v4, v18, v18 quad_perm:[1,0,3,2] row_mask:0xf bank_mask:0xf bound_ctrl:1
	s_nop 1
	v_add_f32_dpp v4, v4, v4 quad_perm:[2,3,0,1] row_mask:0xf bank_mask:0xf bound_ctrl:1
	s_nop 1
	v_add_f32_dpp v4, v4, v4 row_half_mirror row_mask:0xf bank_mask:0xf bound_ctrl:1
	s_nop 1
	v_add_f32_dpp v4, v4, v4 row_mirror row_mask:0xf bank_mask:0xf bound_ctrl:1
	ds_swizzle_b32 v17, v4 offset:swizzle(SWAP,16)
	s_waitcnt lgkmcnt(0)
	v_add_f32_e32 v4, v4, v17
	v_fmamk_f32 v4, v4, 0x3c000000, v227
	v_rsq_f32_e32 v4, v4
	s_nop 0
	v_mul_f32_e32 v1, v1, v4
	v_mul_f32_e32 v1, v79, v1
	v_cvt_pk_bf16_f32 v1, v1, s0
	ds_write_b16 v0, v1
	v_mul_f32_e32 v1, v3, v4
	v_mul_f32_e32 v1, v78, v1
	v_cvt_pk_bf16_f32 v1, v1, s0
	ds_write_b16 v0, v1 offset:64
	v_mul_f32_e32 v1, v16, v4
	v_mul_f32_e32 v1, v49, v1
	v_cvt_pk_bf16_f32 v1, v1, s0
	ds_write_b16 v0, v1 offset:128
	v_mul_f32_e32 v1, v2, v4
	v_mul_f32_e32 v1, v48, v1
	v_cvt_pk_bf16_f32 v1, v1, s0
	ds_write_b16 v0, v1 offset:192
	v_or_b32_e32 v0, 0x900, v76
	v_add_u32_e32 v0, v77, v0
	ds_read_u16 v1, v0
	v_rcp_f32_e32 v2, v73
	ds_read_u16 v3, v0 offset:64
	ds_read_u16 v4, v0 offset:128
	ds_read_u16 v16, v0 offset:192
	s_waitcnt lgkmcnt(3)
	v_lshlrev_b32_e32 v1, 16, v1
	v_mul_f32_e32 v17, v53, v2
	v_fma_f32 v1, -v229, v17, v1
	s_waitcnt lgkmcnt(2)
	v_lshlrev_b32_e32 v3, 16, v3
	v_mul_f32_e32 v17, v37, v2
	v_fma_f32 v3, -v229, v17, v3
	v_mul_f32_e32 v17, v3, v3
	s_waitcnt lgkmcnt(1)
	v_lshlrev_b32_e32 v4, 16, v4
	v_mul_f32_e32 v18, v21, v2
	v_fmac_f32_e32 v17, v1, v1
	v_fma_f32 v4, -v229, v18, v4
	s_waitcnt lgkmcnt(0)
	v_lshlrev_b32_e32 v16, 16, v16
	v_mul_f32_e32 v2, v5, v2
	v_fmac_f32_e32 v17, v4, v4
	v_fma_f32 v2, -v229, v2, v16
	v_fmac_f32_e32 v17, v2, v2
	s_nop 1
	v_add_f32_dpp v5, v17, v17 quad_perm:[1,0,3,2] row_mask:0xf bank_mask:0xf bound_ctrl:1
	s_nop 1
	v_add_f32_dpp v5, v5, v5 quad_perm:[2,3,0,1] row_mask:0xf bank_mask:0xf bound_ctrl:1
	s_nop 1
	v_add_f32_dpp v5, v5, v5 row_half_mirror row_mask:0xf bank_mask:0xf bound_ctrl:1
	s_nop 1
	v_add_f32_dpp v5, v5, v5 row_mirror row_mask:0xf bank_mask:0xf bound_ctrl:1
	ds_swizzle_b32 v16, v5 offset:swizzle(SWAP,16)
	s_waitcnt lgkmcnt(0)
	v_add_f32_e32 v5, v5, v16
	v_fmamk_f32 v5, v5, 0x3c000000, v227
	v_rsq_f32_e32 v5, v5
	s_nop 0
	v_mul_f32_e32 v1, v1, v5
	v_mul_f32_e32 v1, v79, v1
	v_cvt_pk_bf16_f32 v1, v1, s0
	ds_write_b16 v0, v1
	v_mul_f32_e32 v1, v3, v5
	v_mul_f32_e32 v1, v78, v1
	v_cvt_pk_bf16_f32 v1, v1, s0
	ds_write_b16 v0, v1 offset:64
	v_mul_f32_e32 v1, v4, v5
	v_mul_f32_e32 v1, v49, v1
	v_cvt_pk_bf16_f32 v1, v1, s0
	ds_write_b16 v0, v1 offset:128
	v_mul_f32_e32 v1, v2, v5
	v_mul_f32_e32 v1, v48, v1
	v_cvt_pk_bf16_f32 v1, v1, s0
	ds_write_b16 v0, v1 offset:192
	v_or_b32_e32 v0, 0xa00, v76
	v_add_u32_e32 v0, v77, v0
	ds_read_u16 v1, v0
	v_rcp_f32_e32 v2, v74
	ds_read_u16 v3, v0 offset:64
	ds_read_u16 v4, v0 offset:128
	ds_read_u16 v5, v0 offset:192
	s_waitcnt lgkmcnt(3)
	v_lshlrev_b32_e32 v1, 16, v1
	v_mul_f32_e32 v16, v54, v2
	v_fma_f32 v1, -v229, v16, v1
	s_waitcnt lgkmcnt(2)
	v_lshlrev_b32_e32 v3, 16, v3
	v_mul_f32_e32 v16, v38, v2
	v_fma_f32 v3, -v229, v16, v3
	v_mul_f32_e32 v16, v3, v3
	s_waitcnt lgkmcnt(1)
	v_lshlrev_b32_e32 v4, 16, v4
	v_mul_f32_e32 v17, v22, v2
	v_fmac_f32_e32 v16, v1, v1
	v_fma_f32 v4, -v229, v17, v4
	s_waitcnt lgkmcnt(0)
	v_lshlrev_b32_e32 v5, 16, v5
	v_mul_f32_e32 v2, v6, v2
	v_fmac_f32_e32 v16, v4, v4
	v_fma_f32 v2, -v229, v2, v5
	v_fmac_f32_e32 v16, v2, v2
	s_nop 1
	v_add_f32_dpp v5, v16, v16 quad_perm:[1,0,3,2] row_mask:0xf bank_mask:0xf bound_ctrl:1
	s_nop 1
	v_add_f32_dpp v5, v5, v5 quad_perm:[2,3,0,1] row_mask:0xf bank_mask:0xf bound_ctrl:1
	s_nop 1
	v_add_f32_dpp v5, v5, v5 row_half_mirror row_mask:0xf bank_mask:0xf bound_ctrl:1
	s_nop 1
	v_add_f32_dpp v5, v5, v5 row_mirror row_mask:0xf bank_mask:0xf bound_ctrl:1
	ds_swizzle_b32 v6, v5 offset:swizzle(SWAP,16)
	s_waitcnt lgkmcnt(0)
	v_add_f32_e32 v5, v5, v6
	v_fmamk_f32 v5, v5, 0x3c000000, v227
	v_rsq_f32_e32 v5, v5
	s_nop 0
	v_mul_f32_e32 v1, v1, v5
	v_mul_f32_e32 v1, v79, v1
	v_cvt_pk_bf16_f32 v1, v1, s0
	ds_write_b16 v0, v1
	v_mul_f32_e32 v1, v3, v5
	v_mul_f32_e32 v1, v78, v1
	v_cvt_pk_bf16_f32 v1, v1, s0
	ds_write_b16 v0, v1 offset:64
	v_mul_f32_e32 v1, v4, v5
	v_mul_f32_e32 v1, v49, v1
	v_cvt_pk_bf16_f32 v1, v1, s0
	ds_write_b16 v0, v1 offset:128
	v_mul_f32_e32 v1, v2, v5
	v_mul_f32_e32 v1, v48, v1
	v_cvt_pk_bf16_f32 v1, v1, s0
	ds_write_b16 v0, v1 offset:192
	v_or_b32_e32 v0, 0xb00, v76
	v_add_u32_e32 v0, v77, v0
	ds_read_u16 v1, v0
	v_rcp_f32_e32 v2, v75
	ds_read_u16 v3, v0 offset:64
	ds_read_u16 v4, v0 offset:128
	ds_read_u16 v5, v0 offset:192
	s_waitcnt lgkmcnt(3)
	v_lshlrev_b32_e32 v1, 16, v1
	v_mul_f32_e32 v6, v55, v2
	v_fma_f32 v1, -v229, v6, v1
	s_waitcnt lgkmcnt(2)
	v_lshlrev_b32_e32 v3, 16, v3
	v_mul_f32_e32 v6, v39, v2
	v_fma_f32 v3, -v229, v6, v3
	v_mul_f32_e32 v6, v3, v3
	s_waitcnt lgkmcnt(1)
	v_lshlrev_b32_e32 v4, 16, v4
	v_mul_f32_e32 v16, v23, v2
	v_fmac_f32_e32 v6, v1, v1
	v_fma_f32 v4, -v229, v16, v4
	s_waitcnt lgkmcnt(0)
	v_lshlrev_b32_e32 v5, 16, v5
	v_mul_f32_e32 v2, v7, v2
	v_fmac_f32_e32 v6, v4, v4
	v_fma_f32 v2, -v229, v2, v5
	v_fmac_f32_e32 v6, v2, v2
	s_nop 1
	v_add_f32_dpp v5, v6, v6 quad_perm:[1,0,3,2] row_mask:0xf bank_mask:0xf bound_ctrl:1
	s_nop 1
	v_add_f32_dpp v5, v5, v5 quad_perm:[2,3,0,1] row_mask:0xf bank_mask:0xf bound_ctrl:1
	s_nop 1
	v_add_f32_dpp v5, v5, v5 row_half_mirror row_mask:0xf bank_mask:0xf bound_ctrl:1
	s_nop 1
	v_add_f32_dpp v5, v5, v5 row_mirror row_mask:0xf bank_mask:0xf bound_ctrl:1
	ds_swizzle_b32 v6, v5 offset:swizzle(SWAP,16)
	s_waitcnt lgkmcnt(0)
	v_add_f32_e32 v5, v5, v6
	v_fmamk_f32 v5, v5, 0x3c000000, v227
	v_rsq_f32_e32 v5, v5
	s_nop 0
	v_mul_f32_e32 v1, v1, v5
	v_mul_f32_e32 v1, v79, v1
	v_cvt_pk_bf16_f32 v1, v1, s0
	ds_write_b16 v0, v1
	v_mul_f32_e32 v1, v3, v5
	v_mul_f32_e32 v1, v78, v1
	v_cvt_pk_bf16_f32 v1, v1, s0
	ds_write_b16 v0, v1 offset:64
	v_mul_f32_e32 v1, v4, v5
	v_mul_f32_e32 v1, v49, v1
	v_cvt_pk_bf16_f32 v1, v1, s0
	ds_write_b16 v0, v1 offset:128
	v_mul_f32_e32 v1, v2, v5
	v_mul_f32_e32 v1, v48, v1
	v_cvt_pk_bf16_f32 v1, v1, s0
	ds_write_b16 v0, v1 offset:192
	v_or_b32_e32 v0, 0x1000, v76
	v_add_u32_e32 v0, v77, v0
	ds_read_u16 v1, v0
	v_rcp_f32_e32 v2, v68
	ds_read_u16 v3, v0 offset:64
	ds_read_u16 v4, v0 offset:128
	ds_read_u16 v5, v0 offset:192
	s_waitcnt lgkmcnt(3)
	v_lshlrev_b32_e32 v1, 16, v1
	v_mul_f32_e32 v6, v56, v2
	v_fma_f32 v1, -v229, v6, v1
	s_waitcnt lgkmcnt(2)
	v_lshlrev_b32_e32 v3, 16, v3
	v_mul_f32_e32 v6, v40, v2
	v_fma_f32 v3, -v229, v6, v3
	v_mul_f32_e32 v6, v3, v3
	s_waitcnt lgkmcnt(1)
	v_lshlrev_b32_e32 v4, 16, v4
	v_mul_f32_e32 v7, v24, v2
	v_fmac_f32_e32 v6, v1, v1
	v_fma_f32 v4, -v229, v7, v4
	s_waitcnt lgkmcnt(0)
	v_lshlrev_b32_e32 v5, 16, v5
	v_mul_f32_e32 v2, v8, v2
	v_fmac_f32_e32 v6, v4, v4
	v_fma_f32 v2, -v229, v2, v5
	v_fmac_f32_e32 v6, v2, v2
	v_lshlrev_b32_e32 v40, 11, v233
	v_rcp_f32_e32 v8, v66
	v_add_f32_dpp v5, v6, v6 quad_perm:[1,0,3,2] row_mask:0xf bank_mask:0xf bound_ctrl:1
	s_nop 1
	v_add_f32_dpp v5, v5, v5 quad_perm:[2,3,0,1] row_mask:0xf bank_mask:0xf bound_ctrl:1
	s_nop 1
	v_add_f32_dpp v5, v5, v5 row_half_mirror row_mask:0xf bank_mask:0xf bound_ctrl:1
	s_nop 1
	v_add_f32_dpp v5, v5, v5 row_mirror row_mask:0xf bank_mask:0xf bound_ctrl:1
	ds_swizzle_b32 v6, v5 offset:swizzle(SWAP,16)
	s_waitcnt lgkmcnt(0)
	v_add_f32_e32 v5, v5, v6
	v_fmamk_f32 v5, v5, 0x3c000000, v227
	v_rsq_f32_e32 v5, v5
	s_nop 0
	v_mul_f32_e32 v1, v1, v5
	v_mul_f32_e32 v1, v79, v1
	v_cvt_pk_bf16_f32 v1, v1, s0
	ds_write_b16 v0, v1
	v_mul_f32_e32 v1, v3, v5
	v_mul_f32_e32 v1, v78, v1
	v_cvt_pk_bf16_f32 v1, v1, s0
	ds_write_b16 v0, v1 offset:64
	v_mul_f32_e32 v1, v4, v5
	v_mul_f32_e32 v1, v49, v1
	v_cvt_pk_bf16_f32 v1, v1, s0
	ds_write_b16 v0, v1 offset:128
	v_mul_f32_e32 v1, v2, v5
	v_mul_f32_e32 v1, v48, v1
	v_cvt_pk_bf16_f32 v1, v1, s0
	ds_write_b16 v0, v1 offset:192
	v_or_b32_e32 v0, 0x1100, v76
	v_add_u32_e32 v0, v77, v0
	ds_read_u16 v1, v0
	v_rcp_f32_e32 v2, v69
	ds_read_u16 v3, v0 offset:64
	ds_read_u16 v4, v0 offset:128
	ds_read_u16 v5, v0 offset:192
	s_waitcnt lgkmcnt(3)
	v_lshlrev_b32_e32 v1, 16, v1
	v_mul_f32_e32 v6, v57, v2
	v_fma_f32 v1, -v229, v6, v1
	s_waitcnt lgkmcnt(2)
	v_lshlrev_b32_e32 v3, 16, v3
	v_mul_f32_e32 v6, v41, v2
	v_fma_f32 v3, -v229, v6, v3
	v_mul_f32_e32 v6, v3, v3
	s_waitcnt lgkmcnt(1)
	v_lshlrev_b32_e32 v4, 16, v4
	v_mul_f32_e32 v7, v25, v2
	v_fmac_f32_e32 v6, v1, v1
	v_fma_f32 v4, -v229, v7, v4
	s_waitcnt lgkmcnt(0)
	v_lshlrev_b32_e32 v5, 16, v5
	v_mul_f32_e32 v2, v9, v2
	v_fmac_f32_e32 v6, v4, v4
	v_fma_f32 v2, -v229, v2, v5
	v_fmac_f32_e32 v6, v2, v2
	v_mov_b32_e32 v41, v213
	s_nop 0
	v_add_f32_dpp v5, v6, v6 quad_perm:[1,0,3,2] row_mask:0xf bank_mask:0xf bound_ctrl:1
	s_nop 1
	v_add_f32_dpp v5, v5, v5 quad_perm:[2,3,0,1] row_mask:0xf bank_mask:0xf bound_ctrl:1
	s_nop 1
	v_add_f32_dpp v5, v5, v5 row_half_mirror row_mask:0xf bank_mask:0xf bound_ctrl:1
	s_nop 1
	v_add_f32_dpp v5, v5, v5 row_mirror row_mask:0xf bank_mask:0xf bound_ctrl:1
	ds_swizzle_b32 v6, v5 offset:swizzle(SWAP,16)
	s_waitcnt lgkmcnt(0)
	v_add_f32_e32 v5, v5, v6
	v_fmamk_f32 v5, v5, 0x3c000000, v227
	v_rsq_f32_e32 v5, v5
	s_nop 0
	v_mul_f32_e32 v1, v1, v5
	v_mul_f32_e32 v1, v79, v1
	v_cvt_pk_bf16_f32 v1, v1, s0
	ds_write_b16 v0, v1
	v_mul_f32_e32 v1, v3, v5
	v_mul_f32_e32 v1, v78, v1
	v_cvt_pk_bf16_f32 v1, v1, s0
	ds_write_b16 v0, v1 offset:64
	v_mul_f32_e32 v1, v4, v5
	v_mul_f32_e32 v1, v49, v1
	v_cvt_pk_bf16_f32 v1, v1, s0
	ds_write_b16 v0, v1 offset:128
	v_mul_f32_e32 v1, v2, v5
	v_mul_f32_e32 v1, v48, v1
	v_cvt_pk_bf16_f32 v1, v1, s0
	ds_write_b16 v0, v1 offset:192
	v_or_b32_e32 v0, 0x1200, v76
	v_add_u32_e32 v0, v77, v0
	ds_read_u16 v1, v0
	v_rcp_f32_e32 v2, v70
	ds_read_u16 v3, v0 offset:64
	ds_read_u16 v4, v0 offset:128
	ds_read_u16 v5, v0 offset:192
	s_waitcnt lgkmcnt(3)
	v_lshlrev_b32_e32 v1, 16, v1
	v_mul_f32_e32 v6, v58, v2
	v_fma_f32 v1, -v229, v6, v1
	s_waitcnt lgkmcnt(2)
	v_lshlrev_b32_e32 v3, 16, v3
	v_mul_f32_e32 v6, v42, v2
	v_fma_f32 v3, -v229, v6, v3
	v_mul_f32_e32 v6, v3, v3
	s_waitcnt lgkmcnt(1)
	v_lshlrev_b32_e32 v4, 16, v4
	v_mul_f32_e32 v7, v26, v2
	v_fmac_f32_e32 v6, v1, v1
	v_fma_f32 v4, -v229, v7, v4
	s_waitcnt lgkmcnt(0)
	v_lshlrev_b32_e32 v5, 16, v5
	v_mul_f32_e32 v2, v10, v2
	v_fmac_f32_e32 v6, v4, v4
	v_fma_f32 v2, -v229, v2, v5
	v_fmac_f32_e32 v6, v2, v2
	v_rcp_f32_e32 v42, v67
	s_nop 0
	v_add_f32_dpp v5, v6, v6 quad_perm:[1,0,3,2] row_mask:0xf bank_mask:0xf bound_ctrl:1
	s_nop 1
	v_add_f32_dpp v5, v5, v5 quad_perm:[2,3,0,1] row_mask:0xf bank_mask:0xf bound_ctrl:1
	s_nop 1
	v_add_f32_dpp v5, v5, v5 row_half_mirror row_mask:0xf bank_mask:0xf bound_ctrl:1
	s_nop 1
	v_add_f32_dpp v5, v5, v5 row_mirror row_mask:0xf bank_mask:0xf bound_ctrl:1
	ds_swizzle_b32 v6, v5 offset:swizzle(SWAP,16)
	s_waitcnt lgkmcnt(0)
	v_add_f32_e32 v5, v5, v6
	v_fmamk_f32 v5, v5, 0x3c000000, v227
	v_rsq_f32_e32 v5, v5
	s_nop 0
	v_mul_f32_e32 v1, v1, v5
	v_mul_f32_e32 v1, v79, v1
	v_cvt_pk_bf16_f32 v1, v1, s0
	ds_write_b16 v0, v1
	v_mul_f32_e32 v1, v3, v5
	v_mul_f32_e32 v1, v78, v1
	v_cvt_pk_bf16_f32 v1, v1, s0
	ds_write_b16 v0, v1 offset:64
	v_mul_f32_e32 v1, v4, v5
	v_mul_f32_e32 v1, v49, v1
	v_cvt_pk_bf16_f32 v1, v1, s0
	ds_write_b16 v0, v1 offset:128
	v_mul_f32_e32 v1, v2, v5
	v_mul_f32_e32 v1, v48, v1
	v_cvt_pk_bf16_f32 v1, v1, s0
	ds_write_b16 v0, v1 offset:192
	v_or_b32_e32 v0, 0x1300, v76
	v_add_u32_e32 v0, v77, v0
	ds_read_u16 v1, v0
	v_rcp_f32_e32 v2, v71
	ds_read_u16 v3, v0 offset:64
	ds_read_u16 v4, v0 offset:128
	ds_read_u16 v5, v0 offset:192
	s_waitcnt lgkmcnt(3)
	v_lshlrev_b32_e32 v1, 16, v1
	v_mul_f32_e32 v6, v59, v2
	v_fma_f32 v1, -v229, v6, v1
	s_waitcnt lgkmcnt(2)
	v_lshlrev_b32_e32 v3, 16, v3
	v_mul_f32_e32 v6, v43, v2
	v_fma_f32 v3, -v229, v6, v3
	v_mul_f32_e32 v6, v3, v3
	s_waitcnt lgkmcnt(1)
	v_lshlrev_b32_e32 v4, 16, v4
	v_mul_f32_e32 v7, v27, v2
	v_fmac_f32_e32 v6, v1, v1
	v_fma_f32 v4, -v229, v7, v4
	s_waitcnt lgkmcnt(0)
	v_lshlrev_b32_e32 v5, 16, v5
	v_mul_f32_e32 v2, v11, v2
	v_fmac_f32_e32 v6, v4, v4
	v_fma_f32 v2, -v229, v2, v5
	v_fmac_f32_e32 v6, v2, v2
	v_rcp_f32_e32 v7, v64
	s_nop 0
	v_add_f32_dpp v5, v6, v6 quad_perm:[1,0,3,2] row_mask:0xf bank_mask:0xf bound_ctrl:1
	s_nop 1
	v_add_f32_dpp v5, v5, v5 quad_perm:[2,3,0,1] row_mask:0xf bank_mask:0xf bound_ctrl:1
	s_nop 1
	v_add_f32_dpp v5, v5, v5 row_half_mirror row_mask:0xf bank_mask:0xf bound_ctrl:1
	s_nop 1
	v_add_f32_dpp v5, v5, v5 row_mirror row_mask:0xf bank_mask:0xf bound_ctrl:1
	ds_swizzle_b32 v6, v5 offset:swizzle(SWAP,16)
	s_waitcnt lgkmcnt(0)
	v_add_f32_e32 v5, v5, v6
	v_fmamk_f32 v5, v5, 0x3c000000, v227
	v_rsq_f32_e32 v5, v5
	v_rcp_f32_e32 v6, v65
	v_mul_f32_e32 v1, v1, v5
	v_mul_f32_e32 v1, v79, v1
	v_cvt_pk_bf16_f32 v1, v1, s0
	ds_write_b16 v0, v1
	v_mul_f32_e32 v1, v3, v5
	v_mul_f32_e32 v1, v78, v1
	v_cvt_pk_bf16_f32 v1, v1, s0
	ds_write_b16 v0, v1 offset:64
	v_mul_f32_e32 v1, v4, v5
	v_mul_f32_e32 v1, v49, v1
	v_cvt_pk_bf16_f32 v1, v1, s0
	ds_write_b16 v0, v1 offset:128
	v_mul_f32_e32 v1, v2, v5
	v_mul_f32_e32 v1, v48, v1
	v_cvt_pk_bf16_f32 v1, v1, s0
	ds_write_b16 v0, v1 offset:192
	v_or_b32_e32 v0, 0x1800, v76
	v_add_u32_e32 v4, v77, v0
	ds_read_u16 v0, v4
	ds_read_u16 v1, v4 offset:64
	ds_read_u16 v2, v4 offset:128
	ds_read_u16 v3, v4 offset:192
	v_mul_f32_e32 v5, v60, v7
	s_waitcnt lgkmcnt(3)
	v_lshlrev_b32_e32 v0, 16, v0
	v_fma_f32 v5, -v229, v5, v0
	s_waitcnt lgkmcnt(2)
	v_lshlrev_b32_e32 v0, 16, v1
	v_mul_f32_e32 v1, v44, v7
	v_fma_f32 v9, -v229, v1, v0
	v_mul_f32_e32 v0, v9, v9
	s_waitcnt lgkmcnt(1)
	v_lshlrev_b32_e32 v1, 16, v2
	v_mul_f32_e32 v2, v28, v7
	v_fmac_f32_e32 v0, v5, v5
	v_fma_f32 v10, -v229, v2, v1
	s_waitcnt lgkmcnt(0)
	v_lshlrev_b32_e32 v1, 16, v3
	v_mul_f32_e32 v2, v12, v7
	v_fmac_f32_e32 v0, v10, v10
	v_fma_f32 v7, -v229, v2, v1
	v_fmac_f32_e32 v0, v7, v7
	s_nop 1
	v_add_f32_dpp v0, v0, v0 quad_perm:[1,0,3,2] row_mask:0xf bank_mask:0xf bound_ctrl:1
	s_nop 1
	v_add_f32_dpp v0, v0, v0 quad_perm:[2,3,0,1] row_mask:0xf bank_mask:0xf bound_ctrl:1
	s_nop 1
	v_add_f32_dpp v0, v0, v0 row_half_mirror row_mask:0xf bank_mask:0xf bound_ctrl:1
	s_nop 1
	v_add_f32_dpp v2, v0, v0 row_mirror row_mask:0xf bank_mask:0xf bound_ctrl:1
	ds_swizzle_b32 v3, v2 offset:swizzle(SWAP,16)
	v_lshl_add_u64 v[0:1], s[8:9], 0, v[212:213]
	v_lshl_add_u64 v[0:1], v[0:1], 0, v[40:41]
	s_waitcnt lgkmcnt(0)
	v_add_f32_e32 v2, v2, v3
	v_fmamk_f32 v2, v2, 0x3c000000, v227
	v_rsq_f32_e32 v11, v2
	v_add_co_u32_e32 v2, vcc, s5, v0
	s_movk_i32 s5, 0x4000
	v_mul_f32_e32 v5, v5, v11
	v_mul_f32_e32 v5, v79, v5
	v_cvt_pk_bf16_f32 v5, v5, s0
	ds_write_b16 v4, v5
	v_mul_f32_e32 v5, v9, v11
	v_mul_f32_e32 v5, v78, v5
	v_cvt_pk_bf16_f32 v5, v5, s0
	ds_write_b16 v4, v5 offset:64
	v_mul_f32_e32 v5, v10, v11
	v_mul_f32_e32 v5, v49, v5
	v_cvt_pk_bf16_f32 v5, v5, s0
	ds_write_b16 v4, v5 offset:128
	v_mul_f32_e32 v5, v7, v11
	v_mul_f32_e32 v5, v48, v5
	v_cvt_pk_bf16_f32 v5, v5, s0
	ds_write_b16 v4, v5 offset:192
	v_or_b32_e32 v4, 0x1900, v76
	v_add_u32_e32 v7, v77, v4
	ds_read_u16 v4, v7
	v_addc_co_u32_e32 v3, vcc, 0, v1, vcc
	global_load_dwordx4 v[36:39], v[0:1], off nt
	global_load_dwordx4 v[32:35], v[2:3], off nt
	ds_read_u16 v2, v7 offset:64
	ds_read_u16 v3, v7 offset:128
	ds_read_u16 v5, v7 offset:192
	s_waitcnt lgkmcnt(3)
	v_lshlrev_b32_e32 v4, 16, v4
	v_mul_f32_e32 v9, v61, v6
	v_fma_f32 v9, -v229, v9, v4
	s_waitcnt lgkmcnt(2)
	v_lshlrev_b32_e32 v2, 16, v2
	v_mul_f32_e32 v4, v45, v6
	v_fma_f32 v10, -v229, v4, v2
	v_mul_f32_e32 v2, v10, v10
	s_waitcnt lgkmcnt(1)
	v_lshlrev_b32_e32 v3, 16, v3
	v_mul_f32_e32 v4, v29, v6
	v_fmac_f32_e32 v2, v9, v9
	v_fma_f32 v11, -v229, v4, v3
	s_waitcnt lgkmcnt(0)
	v_lshlrev_b32_e32 v3, 16, v5
	v_mul_f32_e32 v4, v13, v6
	v_fmac_f32_e32 v2, v11, v11
	v_fma_f32 v6, -v229, v4, v3
	v_fmac_f32_e32 v2, v6, v6
	s_nop 1
	v_add_f32_dpp v2, v2, v2 quad_perm:[1,0,3,2] row_mask:0xf bank_mask:0xf bound_ctrl:1
	s_nop 1
	v_add_f32_dpp v2, v2, v2 quad_perm:[2,3,0,1] row_mask:0xf bank_mask:0xf bound_ctrl:1
	s_nop 1
	v_add_f32_dpp v2, v2, v2 row_half_mirror row_mask:0xf bank_mask:0xf bound_ctrl:1
	s_nop 1
	v_add_f32_dpp v4, v2, v2 row_mirror row_mask:0xf bank_mask:0xf bound_ctrl:1
	ds_swizzle_b32 v5, v4 offset:swizzle(SWAP,16)
	v_add_co_u32_e32 v2, vcc, s5, v0
	s_movk_i32 s5, 0x6000
	s_nop 0
	v_addc_co_u32_e32 v3, vcc, 0, v1, vcc
	s_waitcnt lgkmcnt(0)
	v_add_f32_e32 v4, v4, v5
	v_fmamk_f32 v4, v4, 0x3c000000, v227
	v_rsq_f32_e32 v12, v4
	v_add_co_u32_e32 v4, vcc, s5, v0
	s_mov_b32 s5, 0x8000
	v_mul_f32_e32 v9, v9, v12
	v_mul_f32_e32 v9, v79, v9
	v_cvt_pk_bf16_f32 v9, v9, s0
	ds_write_b16 v7, v9
	v_mul_f32_e32 v9, v10, v12
	v_mul_f32_e32 v9, v78, v9
	v_cvt_pk_bf16_f32 v9, v9, s0
	v_mul_f32_e32 v6, v6, v12
	ds_write_b16 v7, v9 offset:64
	v_mul_f32_e32 v9, v11, v12
	v_mul_f32_e32 v6, v48, v6
	v_mul_f32_e32 v9, v49, v9
	v_cvt_pk_bf16_f32 v6, v6, s0
	v_cvt_pk_bf16_f32 v9, v9, s0
	ds_write_b16 v7, v6 offset:192
	v_or_b32_e32 v6, 0x1a00, v76
	ds_write_b16 v7, v9 offset:128
	v_add_u32_e32 v6, v77, v6
	ds_read_u16 v7, v6
	v_addc_co_u32_e32 v5, vcc, 0, v1, vcc
	global_load_dwordx4 v[24:27], v[2:3], off nt
	global_load_dwordx4 v[20:23], v[4:5], off nt
	ds_read_u16 v2, v6 offset:64
	ds_read_u16 v3, v6 offset:128
	ds_read_u16 v4, v6 offset:192
	s_waitcnt lgkmcnt(3)
	v_lshlrev_b32_e32 v5, 16, v7
	v_mul_f32_e32 v7, v62, v8
	v_fma_f32 v7, -v229, v7, v5
	s_waitcnt lgkmcnt(2)
	v_lshlrev_b32_e32 v2, 16, v2
	v_mul_f32_e32 v5, v46, v8
	v_fma_f32 v9, -v229, v5, v2
	v_mul_f32_e32 v2, v9, v9
	s_waitcnt lgkmcnt(1)
	v_lshlrev_b32_e32 v3, 16, v3
	v_mul_f32_e32 v5, v30, v8
	v_fmac_f32_e32 v2, v7, v7
	v_fma_f32 v10, -v229, v5, v3
	s_waitcnt lgkmcnt(0)
	v_lshlrev_b32_e32 v3, 16, v4
	v_mul_f32_e32 v4, v14, v8
	v_fmac_f32_e32 v2, v10, v10
	v_fma_f32 v8, -v229, v4, v3
	v_fmac_f32_e32 v2, v8, v8
	s_waitcnt vmcnt(3)
	v_lshlrev_b32_e32 v46, 16, v36
	v_add_f32_dpp v2, v2, v2 quad_perm:[1,0,3,2] row_mask:0xf bank_mask:0xf bound_ctrl:1
	s_nop 1
	v_add_f32_dpp v2, v2, v2 quad_perm:[2,3,0,1] row_mask:0xf bank_mask:0xf bound_ctrl:1
	s_nop 1
	v_add_f32_dpp v2, v2, v2 row_half_mirror row_mask:0xf bank_mask:0xf bound_ctrl:1
	s_nop 1
	v_add_f32_dpp v4, v2, v2 row_mirror row_mask:0xf bank_mask:0xf bound_ctrl:1
	ds_swizzle_b32 v5, v4 offset:swizzle(SWAP,16)
	v_add_co_u32_e32 v2, vcc, s5, v0
	s_mov_b32 s5, 0xa000
	s_nop 0
	v_addc_co_u32_e32 v3, vcc, 0, v1, vcc
	s_waitcnt lgkmcnt(0)
	v_add_f32_e32 v4, v4, v5
	v_fmamk_f32 v4, v4, 0x3c000000, v227
	v_rsq_f32_e32 v11, v4
	v_add_co_u32_e32 v4, vcc, s5, v0
	s_mov_b32 s5, 0xc000
	v_mul_f32_e32 v7, v7, v11
	v_mul_f32_e32 v7, v79, v7
	v_cvt_pk_bf16_f32 v7, v7, s0
	ds_write_b16 v6, v7
	v_mul_f32_e32 v7, v9, v11
	v_mul_f32_e32 v7, v78, v7
	v_cvt_pk_bf16_f32 v7, v7, s0
	ds_write_b16 v6, v7 offset:64
	v_mul_f32_e32 v7, v10, v11
	v_mul_f32_e32 v7, v49, v7
	v_cvt_pk_bf16_f32 v7, v7, s0
	ds_write_b16 v6, v7 offset:128
	v_mul_f32_e32 v7, v8, v11
	v_mul_f32_e32 v7, v48, v7
	v_cvt_pk_bf16_f32 v7, v7, s0
	ds_write_b16 v6, v7 offset:192
	v_or_b32_e32 v6, 0x1b00, v76
	v_add_u32_e32 v12, v77, v6
	ds_read_u16 v6, v12
	v_addc_co_u32_e32 v5, vcc, 0, v1, vcc
	global_load_dwordx4 v[16:19], v[2:3], off nt
	global_load_dwordx4 v[8:11], v[4:5], off nt
	ds_read_u16 v2, v12 offset:64
	ds_read_u16 v3, v12 offset:128
	ds_read_u16 v4, v12 offset:192
	s_waitcnt lgkmcnt(3)
	v_lshlrev_b32_e32 v5, 16, v6
	v_mul_f32_e32 v6, v63, v42
	v_fma_f32 v13, -v229, v6, v5
	s_waitcnt lgkmcnt(2)
	v_lshlrev_b32_e32 v2, 16, v2
	v_mul_f32_e32 v5, v47, v42
	v_fma_f32 v14, -v229, v5, v2
	v_mul_f32_e32 v2, v14, v14
	s_waitcnt lgkmcnt(1)
	v_lshlrev_b32_e32 v3, 16, v3
	v_mul_f32_e32 v5, v31, v42
	v_fmac_f32_e32 v2, v13, v13
	v_fma_f32 v28, -v229, v5, v3
	s_waitcnt lgkmcnt(0)
	v_lshlrev_b32_e32 v3, 16, v4
	v_mul_f32_e32 v4, v15, v42
	v_fmac_f32_e32 v2, v28, v28
	v_fma_f32 v15, -v229, v4, v3
	v_fmac_f32_e32 v2, v15, v15
	s_nop 1
	v_add_f32_dpp v2, v2, v2 quad_perm:[1,0,3,2] row_mask:0xf bank_mask:0xf bound_ctrl:1
	s_nop 1
	v_add_f32_dpp v2, v2, v2 quad_perm:[2,3,0,1] row_mask:0xf bank_mask:0xf bound_ctrl:1
	s_nop 1
	v_add_f32_dpp v2, v2, v2 row_half_mirror row_mask:0xf bank_mask:0xf bound_ctrl:1
	s_nop 1
	v_add_f32_dpp v4, v2, v2 row_mirror row_mask:0xf bank_mask:0xf bound_ctrl:1
	ds_swizzle_b32 v5, v4 offset:swizzle(SWAP,16)
	v_add_co_u32_e32 v2, vcc, s5, v0
	s_mov_b32 s5, 0xe000
	s_nop 0
	v_addc_co_u32_e32 v3, vcc, 0, v1, vcc
	s_waitcnt lgkmcnt(0)
	v_add_f32_e32 v4, v4, v5
	v_fmamk_f32 v4, v4, 0x3c000000, v227
	v_rsq_f32_e32 v29, v4
	v_add_co_u32_e32 v0, vcc, s5, v0
	v_mul_f32_e32 v13, v13, v29
	v_mul_f32_e32 v13, v79, v13
	v_addc_co_u32_e32 v1, vcc, 0, v1, vcc
	v_cvt_pk_bf16_f32 v13, v13, s0
	global_load_dwordx4 v[4:7], v[2:3], off nt
	s_nop 0
	global_load_dwordx4 v[0:3], v[0:1], off nt
	ds_write_b16 v12, v13
	v_mul_f32_e32 v13, v14, v29
	v_mul_f32_e32 v13, v78, v13
	v_cvt_pk_bf16_f32 v13, v13, s0
	ds_write_b16 v12, v13 offset:64
	v_mul_f32_e32 v13, v28, v29
	v_mul_f32_e32 v13, v49, v13
	v_cvt_pk_bf16_f32 v13, v13, s0
	ds_write_b16 v12, v13 offset:128
	v_mul_f32_e32 v13, v15, v29
	v_mul_f32_e32 v13, v48, v13
	v_and_b32_e32 v49, 0xffff0000, v36
	v_mul_f32_e32 v28, 0xbfb8aa3b, v46
	v_cvt_pk_bf16_f32 v13, v13, s0
	v_exp_f32_e32 v36, v28
	v_mul_f32_e32 v28, 0xbfb8aa3b, v49
	ds_write_b16 v12, v13 offset:192
	v_add_u32_e32 v14, s4, v212
	v_exp_f32_e32 v42, v28
	s_waitcnt lgkmcnt(0)
	v_lshl_add_u32 v15, v233, 8, v14
	ds_read_b128 v[28:31], v15
	v_add_f32_e32 v15, 1.0, v36
	v_rcp_f32_e32 v50, v15
	v_add_f32_e32 v15, 1.0, v42
	v_rcp_f32_e32 v51, v15
	v_or_b32_e32 v15, 4, v233
	v_lshl_add_u32 v36, v15, 8, v14
	ds_read_b128 v[42:45], v36
	s_waitcnt lgkmcnt(1)
	v_and_b32_e32 v47, 0xffff0000, v28
	v_lshlrev_b32_e32 v48, 16, v28
	v_lshlrev_b32_e32 v36, 16, v37
	v_pk_mul_f32 v[46:47], v[48:49], v[46:47]
	v_and_b32_e32 v49, 0xffff0000, v37
	v_mul_f32_e32 v28, 0xbfb8aa3b, v36
	v_exp_f32_e32 v37, v28
	v_mul_f32_e32 v28, 0xbfb8aa3b, v49
	v_exp_f32_e32 v48, v28
	v_pk_mul_f32 v[46:47], v[50:51], v[46:47]
	v_add_f32_e32 v37, 1.0, v37
	v_cvt_pk_bf16_f32 v28, v46, v47
	v_rcp_f32_e32 v46, v37
	v_add_f32_e32 v37, 1.0, v48
	v_rcp_f32_e32 v47, v37
	v_and_b32_e32 v37, 0xffff0000, v29
	v_lshlrev_b32_e32 v48, 16, v29
	v_pk_mul_f32 v[36:37], v[48:49], v[36:37]
	v_and_b32_e32 v49, 0xffff0000, v38
	v_pk_mul_f32 v[36:37], v[46:47], v[36:37]
	v_lshlrev_b32_e32 v46, 16, v38
	v_mul_f32_e32 v29, 0xbfb8aa3b, v46
	v_exp_f32_e32 v38, v29
	v_mul_f32_e32 v29, 0xbfb8aa3b, v49
	v_exp_f32_e32 v47, v29
	v_cvt_pk_bf16_f32 v29, v36, v37
	v_add_f32_e32 v36, 1.0, v38
	v_rcp_f32_e32 v36, v36
	v_add_f32_e32 v37, 1.0, v47
	v_rcp_f32_e32 v37, v37
	v_and_b32_e32 v47, 0xffff0000, v30
	v_lshlrev_b32_e32 v48, 16, v30
	v_pk_mul_f32 v[46:47], v[48:49], v[46:47]
	v_lshlrev_b32_e32 v38, 16, v39
	v_pk_mul_f32 v[36:37], v[36:37], v[46:47]
	v_and_b32_e32 v47, 0xffff0000, v39
	v_mul_f32_e32 v30, 0xbfb8aa3b, v38
	v_exp_f32_e32 v39, v30
	v_mul_f32_e32 v30, 0xbfb8aa3b, v47
	v_exp_f32_e32 v46, v30
	v_cvt_pk_bf16_f32 v30, v36, v37
	v_add_f32_e32 v36, 1.0, v39
	v_rcp_f32_e32 v36, v36
	v_add_f32_e32 v37, 1.0, v46
	v_rcp_f32_e32 v37, v37
	v_and_b32_e32 v39, 0xffff0000, v31
	v_lshlrev_b32_e32 v46, 16, v31
	v_pk_mul_f32 v[38:39], v[46:47], v[38:39]
	v_lshl_add_u64 v[12:13], s[6:7], 0, v[212:213]
	v_pk_mul_f32 v[36:37], v[36:37], v[38:39]
	s_waitcnt vmcnt(6)
	v_lshlrev_b32_e32 v38, 16, v32
	v_cvt_pk_bf16_f32 v31, v36, v37
	v_lshl_add_u64 v[36:37], v[12:13], 0, v[40:41]
	v_and_b32_e32 v41, 0xffff0000, v32
	v_mul_f32_e32 v32, 0xbfb8aa3b, v38
	v_mul_f32_e32 v39, 0xbfb8aa3b, v41
	v_exp_f32_e32 v32, v32
	v_exp_f32_e32 v39, v39
	global_store_dwordx4 v[36:37], v[28:31], off
	s_waitcnt lgkmcnt(0)
	v_lshlrev_b32_e32 v40, 16, v42
	v_lshlrev_b32_e32 v212, 11, v15
	v_add_f32_e32 v28, 1.0, v32
	v_add_f32_e32 v29, 1.0, v39
	v_rcp_f32_e32 v28, v28
	v_rcp_f32_e32 v29, v29
	v_and_b32_e32 v39, 0xffff0000, v42
	v_pk_mul_f32 v[30:31], v[40:41], v[38:39]
	s_waitcnt vmcnt(6)
	v_and_b32_e32 v39, 0xffff0000, v24
	v_pk_mul_f32 v[28:29], v[28:29], v[30:31]
	v_lshlrev_b32_e32 v30, 16, v33
	v_and_b32_e32 v33, 0xffff0000, v33
	v_mul_f32_e32 v31, 0xbfb8aa3b, v30
	v_exp_f32_e32 v31, v31
	v_mul_f32_e32 v32, 0xbfb8aa3b, v33
	v_exp_f32_e32 v32, v32
	v_cvt_pk_bf16_f32 v28, v28, v29
	v_add_f32_e32 v29, 1.0, v31
	v_rcp_f32_e32 v36, v29
	v_add_f32_e32 v29, 1.0, v32
	v_rcp_f32_e32 v37, v29
	v_and_b32_e32 v31, 0xffff0000, v43
	v_lshlrev_b32_e32 v32, 16, v43
	v_pk_mul_f32 v[30:31], v[32:33], v[30:31]
	v_lshlrev_b32_e32 v32, 16, v34
	v_pk_mul_f32 v[30:31], v[36:37], v[30:31]
	v_and_b32_e32 v37, 0xffff0000, v34
	v_mul_f32_e32 v29, 0xbfb8aa3b, v32
	v_exp_f32_e32 v33, v29
	v_mul_f32_e32 v29, 0xbfb8aa3b, v37
	v_exp_f32_e32 v34, v29
	v_cvt_pk_bf16_f32 v29, v30, v31
	v_add_f32_e32 v30, 1.0, v33
	v_rcp_f32_e32 v30, v30
	v_add_f32_e32 v31, 1.0, v34
	v_rcp_f32_e32 v31, v31
	v_and_b32_e32 v33, 0xffff0000, v44
	v_lshlrev_b32_e32 v36, 16, v44
	v_pk_mul_f32 v[32:33], v[36:37], v[32:33]
	v_or_b32_e32 v15, 8, v233
	v_pk_mul_f32 v[30:31], v[30:31], v[32:33]
	v_lshlrev_b32_e32 v32, 16, v35
	v_and_b32_e32 v35, 0xffff0000, v35
	v_mul_f32_e32 v33, 0xbfb8aa3b, v32
	v_exp_f32_e32 v33, v33
	v_mul_f32_e32 v34, 0xbfb8aa3b, v35
	v_exp_f32_e32 v34, v34
	v_cvt_pk_bf16_f32 v30, v30, v31
	v_add_f32_e32 v31, 1.0, v33
	v_rcp_f32_e32 v36, v31
	v_add_f32_e32 v31, 1.0, v34
	v_rcp_f32_e32 v37, v31
	v_and_b32_e32 v33, 0xffff0000, v45
	v_lshlrev_b32_e32 v34, 16, v45
	v_pk_mul_f32 v[32:33], v[34:35], v[32:33]
	v_or_b32_e32 v42, 12, v233
	v_pk_mul_f32 v[32:33], v[36:37], v[32:33]
	v_lshlrev_b32_e32 v36, 16, v24
	v_cvt_pk_bf16_f32 v31, v32, v33
	v_lshl_add_u64 v[32:33], v[12:13], 0, v[212:213]
	v_mul_f32_e32 v24, 0xbfb8aa3b, v36
	global_store_dwordx4 v[32:33], v[28:31], off
	v_exp_f32_e32 v24, v24
	v_lshlrev_b32_e32 v212, 11, v15
	v_mul_f32_e32 v29, 0xbfb8aa3b, v39
	v_exp_f32_e32 v32, v29
	v_lshl_add_u32 v28, v15, 8, v14
	ds_read_b128 v[28:31], v28
	v_add_f32_e32 v24, 1.0, v24
	v_rcp_f32_e32 v40, v24
	v_add_f32_e32 v24, 1.0, v32
	v_rcp_f32_e32 v41, v24
	v_lshl_add_u32 v24, v42, 8, v14
	ds_read_b128 v[32:35], v24
	s_waitcnt lgkmcnt(1)
	v_and_b32_e32 v37, 0xffff0000, v28
	v_lshlrev_b32_e32 v38, 16, v28
	v_pk_mul_f32 v[36:37], v[38:39], v[36:37]
	v_lshlrev_b32_e32 v38, 16, v25
	v_pk_mul_f32 v[36:37], v[40:41], v[36:37]
	v_and_b32_e32 v41, 0xffff0000, v25
	v_mul_f32_e32 v24, 0xbfb8aa3b, v38
	v_exp_f32_e32 v25, v24
	v_mul_f32_e32 v24, 0xbfb8aa3b, v41
	v_exp_f32_e32 v28, v24
	v_cvt_pk_bf16_f32 v24, v36, v37
	v_add_f32_e32 v25, 1.0, v25
	v_rcp_f32_e32 v36, v25
	v_add_f32_e32 v25, 1.0, v28
	v_rcp_f32_e32 v37, v25
	v_and_b32_e32 v39, 0xffff0000, v29
	v_lshlrev_b32_e32 v40, 16, v29
	v_pk_mul_f32 v[28:29], v[40:41], v[38:39]
	v_and_b32_e32 v39, 0xffff0000, v26
	v_pk_mul_f32 v[28:29], v[36:37], v[28:29]
	v_lshlrev_b32_e32 v36, 16, v26
	v_mul_f32_e32 v25, 0xbfb8aa3b, v36
	v_exp_f32_e32 v26, v25
	v_mul_f32_e32 v25, 0xbfb8aa3b, v39
	v_exp_f32_e32 v37, v25
	v_cvt_pk_bf16_f32 v25, v28, v29
	v_add_f32_e32 v26, 1.0, v26
	v_rcp_f32_e32 v28, v26
	v_add_f32_e32 v26, 1.0, v37
	v_rcp_f32_e32 v29, v26
	v_and_b32_e32 v37, 0xffff0000, v30
	v_lshlrev_b32_e32 v38, 16, v30
	v_pk_mul_f32 v[36:37], v[38:39], v[36:37]
	v_and_b32_e32 v39, 0xffff0000, v27
	v_pk_mul_f32 v[28:29], v[28:29], v[36:37]
	v_lshlrev_b32_e32 v36, 16, v27
	v_mul_f32_e32 v26, 0xbfb8aa3b, v36
	v_exp_f32_e32 v27, v26
	v_mul_f32_e32 v26, 0xbfb8aa3b, v39
	v_exp_f32_e32 v30, v26
	v_cvt_pk_bf16_f32 v26, v28, v29
	v_add_f32_e32 v27, 1.0, v27
	v_rcp_f32_e32 v28, v27
	v_add_f32_e32 v27, 1.0, v30
	v_rcp_f32_e32 v29, v27
	v_and_b32_e32 v37, 0xffff0000, v31
	v_lshlrev_b32_e32 v38, 16, v31
	v_pk_mul_f32 v[30:31], v[38:39], v[36:37]
	s_waitcnt vmcnt(6)
	v_and_b32_e32 v37, 0xffff0000, v20
	v_pk_mul_f32 v[28:29], v[28:29], v[30:31]
	v_lshlrev_b32_e32 v30, 16, v20
	v_mul_f32_e32 v15, 0xbfb8aa3b, v30
	v_exp_f32_e32 v15, v15
	v_mul_f32_e32 v20, 0xbfb8aa3b, v37
	v_exp_f32_e32 v20, v20
	v_cvt_pk_bf16_f32 v27, v28, v29
	v_lshl_add_u64 v[28:29], v[12:13], 0, v[212:213]
	v_add_f32_e32 v15, 1.0, v15
	global_store_dwordx4 v[28:29], v[24:27], off
	s_waitcnt lgkmcnt(0)
	v_and_b32_e32 v31, 0xffff0000, v32
	v_lshlrev_b32_e32 v36, 16, v32
	v_rcp_f32_e32 v24, v15
	v_add_f32_e32 v15, 1.0, v20
	v_rcp_f32_e32 v25, v15
	v_pk_mul_f32 v[26:27], v[36:37], v[30:31]
	v_and_b32_e32 v29, 0xffff0000, v21
	v_mul_f32_e32 v20, 0xbfb8aa3b, v29
	v_pk_mul_f32 v[24:25], v[24:25], v[26:27]
	v_lshlrev_b32_e32 v26, 16, v21
	v_mul_f32_e32 v15, 0xbfb8aa3b, v26
	v_exp_f32_e32 v15, v15
	v_exp_f32_e32 v21, v20
	v_cvt_pk_bf16_f32 v20, v24, v25
	v_and_b32_e32 v27, 0xffff0000, v33
	v_add_f32_e32 v15, 1.0, v15
	v_rcp_f32_e32 v24, v15
	v_add_f32_e32 v15, 1.0, v21
	v_rcp_f32_e32 v25, v15
	v_lshlrev_b32_e32 v28, 16, v33
	v_pk_mul_f32 v[26:27], v[28:29], v[26:27]
	v_and_b32_e32 v29, 0xffff0000, v22
	v_pk_mul_f32 v[24:25], v[24:25], v[26:27]
	v_lshlrev_b32_e32 v26, 16, v22
	v_mul_f32_e32 v15, 0xbfb8aa3b, v26
	v_exp_f32_e32 v15, v15
	v_mul_f32_e32 v21, 0xbfb8aa3b, v29
	v_exp_f32_e32 v22, v21
	v_cvt_pk_bf16_f32 v21, v24, v25
	v_add_f32_e32 v15, 1.0, v15
	v_rcp_f32_e32 v24, v15
	v_add_f32_e32 v15, 1.0, v22
	v_rcp_f32_e32 v25, v15
	v_and_b32_e32 v27, 0xffff0000, v34
	v_lshlrev_b32_e32 v28, 16, v34
	v_pk_mul_f32 v[26:27], v[28:29], v[26:27]
	v_and_b32_e32 v29, 0xffff0000, v23
	v_pk_mul_f32 v[24:25], v[24:25], v[26:27]
	v_lshlrev_b32_e32 v26, 16, v23
	v_mul_f32_e32 v15, 0xbfb8aa3b, v26
	v_exp_f32_e32 v15, v15
	v_mul_f32_e32 v22, 0xbfb8aa3b, v29
	v_exp_f32_e32 v23, v22
	v_cvt_pk_bf16_f32 v22, v24, v25
	v_add_f32_e32 v15, 1.0, v15
	v_rcp_f32_e32 v24, v15
	v_add_f32_e32 v15, 1.0, v23
	v_rcp_f32_e32 v25, v15
	v_and_b32_e32 v27, 0xffff0000, v35
	v_lshlrev_b32_e32 v28, 16, v35
	v_pk_mul_f32 v[26:27], v[28:29], v[26:27]
	v_lshlrev_b32_e32 v212, 11, v42
	v_pk_mul_f32 v[24:25], v[24:25], v[26:27]
	s_waitcnt vmcnt(6)
	v_lshlrev_b32_e32 v28, 16, v16
	v_cvt_pk_bf16_f32 v23, v24, v25
	v_lshl_add_u64 v[24:25], v[12:13], 0, v[212:213]
	v_and_b32_e32 v31, 0xffff0000, v16
	v_mul_f32_e32 v16, 0xbfb8aa3b, v28
	global_store_dwordx4 v[24:25], v[20:23], off
	v_exp_f32_e32 v16, v16
	v_or_b32_e32 v15, 16, v233
	v_mul_f32_e32 v21, 0xbfb8aa3b, v31
	v_exp_f32_e32 v24, v21
	v_lshl_add_u32 v20, v15, 8, v14
	ds_read_b128 v[20:23], v20
	v_add_f32_e32 v16, 1.0, v16
	v_rcp_f32_e32 v32, v16
	v_add_f32_e32 v16, 1.0, v24
	v_rcp_f32_e32 v33, v16
	v_or_b32_e32 v34, 20, v233
	v_lshl_add_u32 v16, v34, 8, v14
	ds_read_b128 v[24:27], v16
	s_waitcnt lgkmcnt(1)
	v_and_b32_e32 v29, 0xffff0000, v20
	v_lshlrev_b32_e32 v30, 16, v20
	v_pk_mul_f32 v[28:29], v[30:31], v[28:29]
	v_lshlrev_b32_e32 v30, 16, v17
	v_pk_mul_f32 v[28:29], v[32:33], v[28:29]
	v_and_b32_e32 v33, 0xffff0000, v17
	v_mul_f32_e32 v16, 0xbfb8aa3b, v30
	v_exp_f32_e32 v17, v16
	v_mul_f32_e32 v16, 0xbfb8aa3b, v33
	v_exp_f32_e32 v20, v16
	v_cvt_pk_bf16_f32 v16, v28, v29
	v_add_f32_e32 v17, 1.0, v17
	v_rcp_f32_e32 v28, v17
	v_add_f32_e32 v17, 1.0, v20
	v_rcp_f32_e32 v29, v17
	v_and_b32_e32 v31, 0xffff0000, v21
	v_lshlrev_b32_e32 v32, 16, v21
	v_pk_mul_f32 v[20:21], v[32:33], v[30:31]
	v_and_b32_e32 v31, 0xffff0000, v18
	v_pk_mul_f32 v[20:21], v[28:29], v[20:21]
	v_lshlrev_b32_e32 v28, 16, v18
	v_mul_f32_e32 v17, 0xbfb8aa3b, v28
	v_exp_f32_e32 v18, v17
	v_mul_f32_e32 v17, 0xbfb8aa3b, v31
	v_exp_f32_e32 v29, v17
	v_cvt_pk_bf16_f32 v17, v20, v21
	v_add_f32_e32 v18, 1.0, v18
	v_rcp_f32_e32 v20, v18
	v_add_f32_e32 v18, 1.0, v29
	v_rcp_f32_e32 v21, v18
	v_and_b32_e32 v29, 0xffff0000, v22
	v_lshlrev_b32_e32 v30, 16, v22
	v_pk_mul_f32 v[28:29], v[30:31], v[28:29]
	v_and_b32_e32 v31, 0xffff0000, v19
	v_pk_mul_f32 v[20:21], v[20:21], v[28:29]
	v_lshlrev_b32_e32 v28, 16, v19
	v_mul_f32_e32 v18, 0xbfb8aa3b, v28
	v_exp_f32_e32 v19, v18
	v_mul_f32_e32 v18, 0xbfb8aa3b, v31
	v_exp_f32_e32 v22, v18
	v_cvt_pk_bf16_f32 v18, v20, v21
	v_add_f32_e32 v19, 1.0, v19
	v_rcp_f32_e32 v20, v19
	v_add_f32_e32 v19, 1.0, v22
	v_rcp_f32_e32 v21, v19
	v_and_b32_e32 v29, 0xffff0000, v23
	v_lshlrev_b32_e32 v30, 16, v23
	v_pk_mul_f32 v[22:23], v[30:31], v[28:29]
	s_waitcnt vmcnt(6)
	v_and_b32_e32 v29, 0xffff0000, v8
	v_pk_mul_f32 v[20:21], v[20:21], v[22:23]
	v_lshlrev_b32_e32 v22, 16, v8
	v_mul_f32_e32 v8, 0xbfb8aa3b, v22
	v_lshlrev_b32_e32 v212, 11, v15
	v_exp_f32_e32 v8, v8
	v_mul_f32_e32 v15, 0xbfb8aa3b, v29
	v_exp_f32_e32 v15, v15
	v_cvt_pk_bf16_f32 v19, v20, v21
	v_lshl_add_u64 v[20:21], v[12:13], 0, v[212:213]
	v_add_f32_e32 v8, 1.0, v8
	global_store_dwordx4 v[20:21], v[16:19], off
	s_waitcnt lgkmcnt(0)
	v_and_b32_e32 v23, 0xffff0000, v24
	v_lshlrev_b32_e32 v28, 16, v24
	v_rcp_f32_e32 v16, v8
	v_add_f32_e32 v8, 1.0, v15
	v_rcp_f32_e32 v17, v8
	v_pk_mul_f32 v[18:19], v[28:29], v[22:23]
	v_and_b32_e32 v21, 0xffff0000, v9
	v_lshlrev_b32_e32 v20, 16, v25
	v_pk_mul_f32 v[16:17], v[16:17], v[18:19]
	v_lshlrev_b32_e32 v18, 16, v9
	v_mul_f32_e32 v8, 0xbfb8aa3b, v18
	v_exp_f32_e32 v9, v8
	v_mul_f32_e32 v8, 0xbfb8aa3b, v21
	v_exp_f32_e32 v15, v8
	v_cvt_pk_bf16_f32 v8, v16, v17
	v_add_f32_e32 v9, 1.0, v9
	v_rcp_f32_e32 v16, v9
	v_add_f32_e32 v9, 1.0, v15
	v_rcp_f32_e32 v17, v9
	v_and_b32_e32 v19, 0xffff0000, v25
	v_pk_mul_f32 v[18:19], v[20:21], v[18:19]
	v_and_b32_e32 v21, 0xffff0000, v10
	v_pk_mul_f32 v[16:17], v[16:17], v[18:19]
	v_lshlrev_b32_e32 v18, 16, v10
	v_mul_f32_e32 v9, 0xbfb8aa3b, v18
	v_exp_f32_e32 v10, v9
	v_mul_f32_e32 v9, 0xbfb8aa3b, v21
	v_exp_f32_e32 v15, v9
	v_cvt_pk_bf16_f32 v9, v16, v17
	v_add_f32_e32 v10, 1.0, v10
	v_rcp_f32_e32 v16, v10
	v_add_f32_e32 v10, 1.0, v15
	v_rcp_f32_e32 v17, v10
	v_and_b32_e32 v19, 0xffff0000, v26
	v_lshlrev_b32_e32 v20, 16, v26
	v_pk_mul_f32 v[18:19], v[20:21], v[18:19]
	v_and_b32_e32 v21, 0xffff0000, v11
	v_pk_mul_f32 v[16:17], v[16:17], v[18:19]
	v_lshlrev_b32_e32 v18, 16, v11
	v_mul_f32_e32 v10, 0xbfb8aa3b, v18
	v_exp_f32_e32 v11, v10
	v_mul_f32_e32 v10, 0xbfb8aa3b, v21
	v_exp_f32_e32 v15, v10
	v_cvt_pk_bf16_f32 v10, v16, v17
	v_add_f32_e32 v11, 1.0, v11
	v_rcp_f32_e32 v16, v11
	v_add_f32_e32 v11, 1.0, v15
	v_rcp_f32_e32 v17, v11
	v_and_b32_e32 v19, 0xffff0000, v27
	v_lshlrev_b32_e32 v20, 16, v27
	v_pk_mul_f32 v[18:19], v[20:21], v[18:19]
	v_lshlrev_b32_e32 v212, 11, v34
	v_pk_mul_f32 v[16:17], v[16:17], v[18:19]
	s_waitcnt vmcnt(6)
	v_lshlrev_b32_e32 v18, 16, v4
	v_cvt_pk_bf16_f32 v11, v16, v17
	v_lshl_add_u64 v[16:17], v[12:13], 0, v[212:213]
	v_and_b32_e32 v21, 0xffff0000, v4
	v_mul_f32_e32 v4, 0xbfb8aa3b, v18
	global_store_dwordx4 v[16:17], v[8:11], off
	v_exp_f32_e32 v4, v4
	v_or_b32_e32 v24, 24, v233
	v_mul_f32_e32 v9, 0xbfb8aa3b, v21
	v_exp_f32_e32 v15, v9
	v_lshl_add_u32 v8, v24, 8, v14
	ds_read_b128 v[8:11], v8
	v_add_f32_e32 v4, 1.0, v4
	v_rcp_f32_e32 v22, v4
	v_add_f32_e32 v4, 1.0, v15
	v_rcp_f32_e32 v23, v4
	v_or_b32_e32 v25, 28, v233
	v_lshl_add_u32 v4, v25, 8, v14
	ds_read_b128 v[14:17], v4
	s_waitcnt lgkmcnt(1)
	v_and_b32_e32 v19, 0xffff0000, v8
	v_lshlrev_b32_e32 v20, 16, v8
	v_pk_mul_f32 v[18:19], v[20:21], v[18:19]
	v_lshlrev_b32_e32 v20, 16, v5
	v_pk_mul_f32 v[18:19], v[22:23], v[18:19]
	v_and_b32_e32 v23, 0xffff0000, v5
	v_mul_f32_e32 v4, 0xbfb8aa3b, v20
	v_exp_f32_e32 v5, v4
	v_mul_f32_e32 v4, 0xbfb8aa3b, v23
	v_exp_f32_e32 v8, v4
	v_cvt_pk_bf16_f32 v4, v18, v19
	v_add_f32_e32 v5, 1.0, v5
	v_rcp_f32_e32 v18, v5
	v_add_f32_e32 v5, 1.0, v8
	v_rcp_f32_e32 v19, v5
	v_and_b32_e32 v21, 0xffff0000, v9
	v_lshlrev_b32_e32 v22, 16, v9
	v_pk_mul_f32 v[8:9], v[22:23], v[20:21]
	v_and_b32_e32 v21, 0xffff0000, v6
	v_pk_mul_f32 v[8:9], v[18:19], v[8:9]
	v_lshlrev_b32_e32 v18, 16, v6
	v_mul_f32_e32 v5, 0xbfb8aa3b, v18
	v_exp_f32_e32 v6, v5
	v_mul_f32_e32 v5, 0xbfb8aa3b, v21
	v_exp_f32_e32 v19, v5
	v_cvt_pk_bf16_f32 v5, v8, v9
	v_add_f32_e32 v6, 1.0, v6
	v_rcp_f32_e32 v8, v6
	v_add_f32_e32 v6, 1.0, v19
	v_rcp_f32_e32 v9, v6
	v_and_b32_e32 v19, 0xffff0000, v10
	v_lshlrev_b32_e32 v20, 16, v10
	v_pk_mul_f32 v[18:19], v[20:21], v[18:19]
	v_and_b32_e32 v21, 0xffff0000, v7
	v_pk_mul_f32 v[8:9], v[8:9], v[18:19]
	v_lshlrev_b32_e32 v18, 16, v7
	v_mul_f32_e32 v6, 0xbfb8aa3b, v18
	v_exp_f32_e32 v7, v6
	v_mul_f32_e32 v6, 0xbfb8aa3b, v21
	v_exp_f32_e32 v10, v6
	v_cvt_pk_bf16_f32 v6, v8, v9
	v_add_f32_e32 v7, 1.0, v7
	v_rcp_f32_e32 v8, v7
	v_add_f32_e32 v7, 1.0, v10
	v_rcp_f32_e32 v9, v7
	v_and_b32_e32 v19, 0xffff0000, v11
	v_lshlrev_b32_e32 v20, 16, v11
	v_pk_mul_f32 v[10:11], v[20:21], v[18:19]
	s_waitcnt vmcnt(6)
	v_and_b32_e32 v19, 0xffff0000, v0
	v_pk_mul_f32 v[8:9], v[8:9], v[10:11]
	v_lshlrev_b32_e32 v10, 16, v0
	v_mul_f32_e32 v0, 0xbfb8aa3b, v10
	v_exp_f32_e32 v0, v0
	v_mul_f32_e32 v11, 0xbfb8aa3b, v19
	v_exp_f32_e32 v11, v11
	v_lshlrev_b32_e32 v212, 11, v24
	v_cvt_pk_bf16_f32 v7, v8, v9
	v_lshl_add_u64 v[8:9], v[12:13], 0, v[212:213]
	v_add_f32_e32 v0, 1.0, v0
	global_store_dwordx4 v[8:9], v[4:7], off
	s_waitcnt lgkmcnt(0)
	v_lshlrev_b32_e32 v18, 16, v14
	v_and_b32_e32 v9, 0xffff0000, v1
	v_rcp_f32_e32 v4, v0
	v_add_f32_e32 v0, 1.0, v11
	v_rcp_f32_e32 v5, v0
	v_and_b32_e32 v11, 0xffff0000, v14
	v_pk_mul_f32 v[6:7], v[18:19], v[10:11]
	v_lshlrev_b32_e32 v8, 16, v15
	v_pk_mul_f32 v[4:5], v[4:5], v[6:7]
	v_lshlrev_b32_e32 v6, 16, v1
	v_mul_f32_e32 v0, 0xbfb8aa3b, v6
	v_exp_f32_e32 v1, v0
	v_mul_f32_e32 v0, 0xbfb8aa3b, v9
	v_exp_f32_e32 v7, v0
	v_cvt_pk_bf16_f32 v0, v4, v5
	v_add_f32_e32 v1, 1.0, v1
	v_rcp_f32_e32 v4, v1
	v_add_f32_e32 v1, 1.0, v7
	v_rcp_f32_e32 v5, v1
	v_and_b32_e32 v7, 0xffff0000, v15
	v_pk_mul_f32 v[6:7], v[8:9], v[6:7]
	v_and_b32_e32 v9, 0xffff0000, v2
	v_pk_mul_f32 v[4:5], v[4:5], v[6:7]
	v_lshlrev_b32_e32 v6, 16, v2
	v_mul_f32_e32 v1, 0xbfb8aa3b, v6
	v_exp_f32_e32 v2, v1
	v_mul_f32_e32 v1, 0xbfb8aa3b, v9
	v_exp_f32_e32 v7, v1
	v_cvt_pk_bf16_f32 v1, v4, v5
	v_add_f32_e32 v2, 1.0, v2
	v_rcp_f32_e32 v4, v2
	v_add_f32_e32 v2, 1.0, v7
	v_rcp_f32_e32 v5, v2
	v_and_b32_e32 v7, 0xffff0000, v16
	v_lshlrev_b32_e32 v8, 16, v16
	v_pk_mul_f32 v[6:7], v[8:9], v[6:7]
	v_and_b32_e32 v9, 0xffff0000, v3
	v_pk_mul_f32 v[4:5], v[4:5], v[6:7]
	v_lshlrev_b32_e32 v6, 16, v3
	v_mul_f32_e32 v2, 0xbfb8aa3b, v6
	v_exp_f32_e32 v3, v2
	v_mul_f32_e32 v2, 0xbfb8aa3b, v9
	v_exp_f32_e32 v7, v2
	v_cvt_pk_bf16_f32 v2, v4, v5
	v_add_f32_e32 v3, 1.0, v3
	v_rcp_f32_e32 v4, v3
	v_add_f32_e32 v3, 1.0, v7
	v_rcp_f32_e32 v5, v3
	v_and_b32_e32 v7, 0xffff0000, v17
	v_lshlrev_b32_e32 v8, 16, v17
	v_pk_mul_f32 v[6:7], v[8:9], v[6:7]
	v_lshlrev_b32_e32 v212, 11, v25
	v_pk_mul_f32 v[4:5], v[4:5], v[6:7]
	s_nop 0
	v_cvt_pk_bf16_f32 v3, v4, v5
	v_lshl_add_u64 v[4:5], v[12:13], 0, v[212:213]
	global_store_dwordx4 v[4:5], v[0:3], off
	s_waitcnt lgkmcnt(0)
	s_barrier
	s_cbranch_scc1 .LBB0_1488
